# adds a priority raise for waves 4-7 during the FFN-up epilogue (reset before the next tile)
# baseline (speedup 1.0000x reference)
; #define PG8_BAR __builtin_amdgcn_s_barrier()
; template <class Epi, bool HALO>
; __device__ __forceinline__ void gemm_phase(PG8_LAS unsigned char* lds, const Gemm g, const StaticOrder& S, const Epi& E, const int tid) {
;     ...
;         if (wr == 0) PG8_BAR;
;         E(acc, cur, wr, wc, fr, fq);
.LBB0_43:
	v_readfirstlane_b32 s21, v220
	s_cmp_lt_u32 s21, 0x100
	s_cbranch_scc1 .Lprio_g3_done
	s_setprio 1

; #define PG8_BAR __builtin_amdgcn_s_barrier()
; template <class Epi, bool HALO>
; __device__ __forceinline__ void gemm_phase(PG8_LAS unsigned char* lds, const Gemm g, const StaticOrder& S, const Epi& E, const int tid) {
;     ...
;         E(acc, cur, wr, wc, fr, fq);
;         if (!has_next) break;
; #pragma unroll
;         for (int a = 0; a < 2; ++a)
; #pragma unroll
;             for (int b = 0; b < 2; ++b)
; #pragma unroll
;                 for (int m = 0; m < 4; ++m)
; #pragma unroll
;                     for (int n = 0; n < 2; ++n) acc[a][b][m][n] = (f32x4){0.f, 0.f, 0.f, 0.f};
;         cur = nxt; cA = nA; cB = nB; ++ui;
;         if (wr == 1) PG8_BAR;
.LBB0_59:
	s_setprio 0
	s_or_b64 exec, exec, s[34:35]
	s_and_b64 vcc, exec, s[42:43]
	s_mov_b64 s[34:35], -1
	s_cbranch_vccnz .LBB0_34
	s_andn2_b64 vcc, exec, s[14:15]
	s_cbranch_vccnz .LBB0_33
	s_barrier
	s_branch .LBB0_33
